# w_in epilogue: GELU tiles with folded constants, scalar f32 ops (x*x, fma with c2 and c1, x*p, exp, +1, rcp, x*r: 9.5 slots per element instead of 11.5)
# baseline (speedup 1.0000x reference)
.Lwin_act1:
	v_mul_f32_e32 v128, v124, v124
	v_mul_f32_e32 v129, v125, v125
	v_mul_f32_e32 v130, v126, v126
	v_mul_f32_e32 v131, v127, v127
	v_mul_f32_e32 v132, v120, v120
	v_mul_f32_e32 v133, v121, v121
	v_mul_f32_e32 v134, v122, v122
	v_mul_f32_e32 v135, v123, v123
	v_fma_f32 v128, v128, s98, v250
	v_fma_f32 v129, v129, s98, v250
	v_fma_f32 v130, v130, s98, v250
	v_fma_f32 v131, v131, s98, v250
	v_fma_f32 v132, v132, s98, v250
	v_fma_f32 v133, v133, s98, v250
	v_fma_f32 v134, v134, s98, v250
	v_fma_f32 v135, v135, s98, v250
	v_mul_f32_e32 v128, v124, v128
	v_mul_f32_e32 v129, v125, v129
	v_mul_f32_e32 v130, v126, v130
	v_mul_f32_e32 v131, v127, v131
	v_mul_f32_e32 v132, v120, v132
	v_mul_f32_e32 v133, v121, v133
	v_mul_f32_e32 v134, v122, v134
	v_mul_f32_e32 v135, v123, v135
	v_exp_f32_e32 v128, v128
	v_exp_f32_e32 v129, v129
	v_exp_f32_e32 v130, v130
	v_exp_f32_e32 v131, v131
	v_exp_f32_e32 v132, v132
	v_exp_f32_e32 v133, v133
	v_exp_f32_e32 v134, v134
	v_exp_f32_e32 v135, v135
	v_add_f32_e32 v128, 1.0, v128
	v_add_f32_e32 v129, 1.0, v129
	v_add_f32_e32 v130, 1.0, v130
	v_add_f32_e32 v131, 1.0, v131
	v_add_f32_e32 v132, 1.0, v132
	v_add_f32_e32 v133, 1.0, v133
	v_add_f32_e32 v134, 1.0, v134
	v_add_f32_e32 v135, 1.0, v135
	v_rcp_f32_e32 v128, v128
	v_rcp_f32_e32 v129, v129
	v_rcp_f32_e32 v130, v130
	v_rcp_f32_e32 v131, v131
	v_rcp_f32_e32 v132, v132
	v_rcp_f32_e32 v133, v133
	v_rcp_f32_e32 v134, v134
	v_rcp_f32_e32 v135, v135
	v_mul_f32_e32 v128, v124, v128
	v_mul_f32_e32 v129, v125, v129
	v_mul_f32_e32 v130, v126, v130
	v_mul_f32_e32 v131, v127, v131
	v_mul_f32_e32 v132, v120, v132
	v_mul_f32_e32 v133, v121, v133
	v_mul_f32_e32 v134, v122, v134
	v_mul_f32_e32 v135, v123, v135
	v_cvt_pk_bf16_f32 v128, v128, v129
	v_cvt_pk_bf16_f32 v129, v130, v131
	v_cvt_pk_bf16_f32 v130, v132, v133
	v_cvt_pk_bf16_f32 v131, v134, v135
	global_store_dwordx4 v174, v[128:131], s[60:61]
	v_mul_f32_e32 v120, v116, v116
	v_mul_f32_e32 v121, v117, v117
	v_mul_f32_e32 v122, v118, v118
	v_mul_f32_e32 v123, v119, v119
	v_mul_f32_e32 v124, v112, v112
	v_mul_f32_e32 v125, v113, v113
	v_mul_f32_e32 v126, v114, v114
	v_mul_f32_e32 v127, v115, v115
	v_fma_f32 v120, v120, s98, v250
	v_fma_f32 v121, v121, s98, v250
	v_fma_f32 v122, v122, s98, v250
	v_fma_f32 v123, v123, s98, v250
	v_fma_f32 v124, v124, s98, v250
	v_fma_f32 v125, v125, s98, v250
	v_fma_f32 v126, v126, s98, v250
	v_fma_f32 v127, v127, s98, v250
	v_mul_f32_e32 v120, v116, v120
	v_mul_f32_e32 v121, v117, v121
	v_mul_f32_e32 v122, v118, v122
	v_mul_f32_e32 v123, v119, v123
	v_mul_f32_e32 v124, v112, v124
	v_mul_f32_e32 v125, v113, v125
	v_mul_f32_e32 v126, v114, v126
	v_mul_f32_e32 v127, v115, v127
	v_exp_f32_e32 v120, v120
	v_exp_f32_e32 v121, v121
	v_exp_f32_e32 v122, v122
	v_exp_f32_e32 v123, v123
	v_exp_f32_e32 v124, v124
	v_exp_f32_e32 v125, v125
	v_exp_f32_e32 v126, v126
	v_exp_f32_e32 v127, v127
	v_add_f32_e32 v120, 1.0, v120
	v_add_f32_e32 v121, 1.0, v121
	v_add_f32_e32 v122, 1.0, v122
	v_add_f32_e32 v123, 1.0, v123
	v_add_f32_e32 v124, 1.0, v124
	v_add_f32_e32 v125, 1.0, v125
	v_add_f32_e32 v126, 1.0, v126
	v_add_f32_e32 v127, 1.0, v127
	v_rcp_f32_e32 v120, v120
	v_rcp_f32_e32 v121, v121
	v_rcp_f32_e32 v122, v122
	v_rcp_f32_e32 v123, v123
	v_rcp_f32_e32 v124, v124
	v_rcp_f32_e32 v125, v125
	v_rcp_f32_e32 v126, v126
	v_rcp_f32_e32 v127, v127
	v_mul_f32_e32 v120, v116, v120
	v_mul_f32_e32 v121, v117, v121
	v_mul_f32_e32 v122, v118, v122
	v_mul_f32_e32 v123, v119, v123
	v_mul_f32_e32 v124, v112, v124
	v_mul_f32_e32 v125, v113, v125
	v_mul_f32_e32 v126, v114, v126
	v_mul_f32_e32 v127, v115, v127
	v_cvt_pk_bf16_f32 v120, v120, v121
	v_cvt_pk_bf16_f32 v121, v122, v123
	v_cvt_pk_bf16_f32 v122, v124, v125
	v_cvt_pk_bf16_f32 v123, v126, v127
	global_store_dwordx4 v174, v[120:123], s[60:61] offset:256
	s_add_u32 s60, s60, s64
	s_addc_u32 s61, s61, 0
	v_mul_f32_e32 v112, v108, v108
	v_mul_f32_e32 v113, v109, v109
	v_mul_f32_e32 v114, v110, v110
	v_mul_f32_e32 v115, v111, v111
	v_mul_f32_e32 v116, v104, v104
	v_mul_f32_e32 v117, v105, v105
	v_mul_f32_e32 v118, v106, v106
	v_mul_f32_e32 v119, v107, v107
	v_fma_f32 v112, v112, s98, v250
	v_fma_f32 v113, v113, s98, v250
	v_fma_f32 v114, v114, s98, v250
	v_fma_f32 v115, v115, s98, v250
	v_fma_f32 v116, v116, s98, v250
	v_fma_f32 v117, v117, s98, v250
	v_fma_f32 v118, v118, s98, v250
	v_fma_f32 v119, v119, s98, v250
	v_mul_f32_e32 v112, v108, v112
	v_mul_f32_e32 v113, v109, v113
	v_mul_f32_e32 v114, v110, v114
	v_mul_f32_e32 v115, v111, v115
	v_mul_f32_e32 v116, v104, v116
	v_mul_f32_e32 v117, v105, v117
	v_mul_f32_e32 v118, v106, v118
	v_mul_f32_e32 v119, v107, v119
	v_exp_f32_e32 v112, v112
	v_exp_f32_e32 v113, v113
	v_exp_f32_e32 v114, v114
	v_exp_f32_e32 v115, v115
	v_exp_f32_e32 v116, v116
	v_exp_f32_e32 v117, v117
	v_exp_f32_e32 v118, v118
	v_exp_f32_e32 v119, v119
	v_add_f32_e32 v112, 1.0, v112
	v_add_f32_e32 v113, 1.0, v113
	v_add_f32_e32 v114, 1.0, v114
	v_add_f32_e32 v115, 1.0, v115
	v_add_f32_e32 v116, 1.0, v116
	v_add_f32_e32 v117, 1.0, v117
	v_add_f32_e32 v118, 1.0, v118
	v_add_f32_e32 v119, 1.0, v119
	v_rcp_f32_e32 v112, v112
	v_rcp_f32_e32 v113, v113
	v_rcp_f32_e32 v114, v114
	v_rcp_f32_e32 v115, v115
	v_rcp_f32_e32 v116, v116
	v_rcp_f32_e32 v117, v117
	v_rcp_f32_e32 v118, v118
	v_rcp_f32_e32 v119, v119
	v_mul_f32_e32 v112, v108, v112
	v_mul_f32_e32 v113, v109, v113
	v_mul_f32_e32 v114, v110, v114
	v_mul_f32_e32 v115, v111, v115
	v_mul_f32_e32 v116, v104, v116
	v_mul_f32_e32 v117, v105, v117
	v_mul_f32_e32 v118, v106, v118
	v_mul_f32_e32 v119, v107, v119
	v_cvt_pk_bf16_f32 v112, v112, v113
	v_cvt_pk_bf16_f32 v113, v114, v115
	v_cvt_pk_bf16_f32 v114, v116, v117
	v_cvt_pk_bf16_f32 v115, v118, v119
	global_store_dwordx4 v174, v[112:115], s[60:61]
	v_mul_f32_e32 v104, v100, v100
	v_mul_f32_e32 v105, v101, v101
	v_mul_f32_e32 v106, v102, v102
	v_mul_f32_e32 v107, v103, v103
	v_mul_f32_e32 v108, v96, v96
	v_mul_f32_e32 v109, v97, v97
	v_mul_f32_e32 v110, v98, v98
	v_mul_f32_e32 v111, v99, v99
	v_fma_f32 v104, v104, s98, v250
	v_fma_f32 v105, v105, s98, v250
	v_fma_f32 v106, v106, s98, v250
	v_fma_f32 v107, v107, s98, v250
	v_fma_f32 v108, v108, s98, v250
	v_fma_f32 v109, v109, s98, v250
	v_fma_f32 v110, v110, s98, v250
	v_fma_f32 v111, v111, s98, v250
	v_mul_f32_e32 v104, v100, v104
	v_mul_f32_e32 v105, v101, v105
	v_mul_f32_e32 v106, v102, v106
	v_mul_f32_e32 v107, v103, v107
	v_mul_f32_e32 v108, v96, v108
	v_mul_f32_e32 v109, v97, v109
	v_mul_f32_e32 v110, v98, v110
	v_mul_f32_e32 v111, v99, v111
	v_exp_f32_e32 v104, v104
	v_exp_f32_e32 v105, v105
	v_exp_f32_e32 v106, v106
	v_exp_f32_e32 v107, v107
	v_exp_f32_e32 v108, v108
	v_exp_f32_e32 v109, v109
	v_exp_f32_e32 v110, v110
	v_exp_f32_e32 v111, v111
	v_add_f32_e32 v104, 1.0, v104
	v_add_f32_e32 v105, 1.0, v105
	v_add_f32_e32 v106, 1.0, v106
	v_add_f32_e32 v107, 1.0, v107
	v_add_f32_e32 v108, 1.0, v108
	v_add_f32_e32 v109, 1.0, v109
	v_add_f32_e32 v110, 1.0, v110
	v_add_f32_e32 v111, 1.0, v111
	v_rcp_f32_e32 v104, v104
	v_rcp_f32_e32 v105, v105
	v_rcp_f32_e32 v106, v106
	v_rcp_f32_e32 v107, v107
	v_rcp_f32_e32 v108, v108
	v_rcp_f32_e32 v109, v109
	v_rcp_f32_e32 v110, v110
	v_rcp_f32_e32 v111, v111
	v_mul_f32_e32 v104, v100, v104
	v_mul_f32_e32 v105, v101, v105
	v_mul_f32_e32 v106, v102, v106
	v_mul_f32_e32 v107, v103, v107
	v_mul_f32_e32 v108, v96, v108
	v_mul_f32_e32 v109, v97, v109
	v_mul_f32_e32 v110, v98, v110
	v_mul_f32_e32 v111, v99, v111
	v_cvt_pk_bf16_f32 v104, v104, v105
	v_cvt_pk_bf16_f32 v105, v106, v107
	v_cvt_pk_bf16_f32 v106, v108, v109
	v_cvt_pk_bf16_f32 v107, v110, v111
	global_store_dwordx4 v174, v[104:107], s[60:61] offset:256
	s_add_u32 s60, s60, s64
	s_addc_u32 s61, s61, 0
	v_mul_f32_e32 v96, v92, v92
	v_mul_f32_e32 v97, v93, v93
	v_mul_f32_e32 v98, v94, v94
	v_mul_f32_e32 v99, v95, v95
	v_mul_f32_e32 v100, v88, v88
	v_mul_f32_e32 v101, v89, v89
	v_mul_f32_e32 v102, v90, v90
	v_mul_f32_e32 v103, v91, v91
	v_fma_f32 v96, v96, s98, v250
	v_fma_f32 v97, v97, s98, v250
	v_fma_f32 v98, v98, s98, v250
	v_fma_f32 v99, v99, s98, v250
	v_fma_f32 v100, v100, s98, v250
	v_fma_f32 v101, v101, s98, v250
	v_fma_f32 v102, v102, s98, v250
	v_fma_f32 v103, v103, s98, v250
	v_mul_f32_e32 v96, v92, v96
	v_mul_f32_e32 v97, v93, v97
	v_mul_f32_e32 v98, v94, v98
	v_mul_f32_e32 v99, v95, v99
	v_mul_f32_e32 v100, v88, v100
	v_mul_f32_e32 v101, v89, v101
	v_mul_f32_e32 v102, v90, v102
	v_mul_f32_e32 v103, v91, v103
	v_exp_f32_e32 v96, v96
	v_exp_f32_e32 v97, v97
	v_exp_f32_e32 v98, v98
	v_exp_f32_e32 v99, v99
	v_exp_f32_e32 v100, v100
	v_exp_f32_e32 v101, v101
	v_exp_f32_e32 v102, v102
	v_exp_f32_e32 v103, v103
	v_add_f32_e32 v96, 1.0, v96
	v_add_f32_e32 v97, 1.0, v97
	v_add_f32_e32 v98, 1.0, v98
	v_add_f32_e32 v99, 1.0, v99
	v_add_f32_e32 v100, 1.0, v100
	v_add_f32_e32 v101, 1.0, v101
	v_add_f32_e32 v102, 1.0, v102
	v_add_f32_e32 v103, 1.0, v103
	v_rcp_f32_e32 v96, v96
	v_rcp_f32_e32 v97, v97
	v_rcp_f32_e32 v98, v98
	v_rcp_f32_e32 v99, v99
	v_rcp_f32_e32 v100, v100
	v_rcp_f32_e32 v101, v101
	v_rcp_f32_e32 v102, v102
	v_rcp_f32_e32 v103, v103
	v_mul_f32_e32 v96, v92, v96
	v_mul_f32_e32 v97, v93, v97
	v_mul_f32_e32 v98, v94, v98
	v_mul_f32_e32 v99, v95, v99
	v_mul_f32_e32 v100, v88, v100
	v_mul_f32_e32 v101, v89, v101
	v_mul_f32_e32 v102, v90, v102
	v_mul_f32_e32 v103, v91, v103
	v_cvt_pk_bf16_f32 v96, v96, v97
	v_cvt_pk_bf16_f32 v97, v98, v99
	v_cvt_pk_bf16_f32 v98, v100, v101
	v_cvt_pk_bf16_f32 v99, v102, v103
	global_store_dwordx4 v174, v[96:99], s[60:61]
	v_mul_f32_e32 v88, v84, v84
	v_mul_f32_e32 v89, v85, v85
	v_mul_f32_e32 v90, v86, v86
	v_mul_f32_e32 v91, v87, v87
	v_mul_f32_e32 v92, v80, v80
	v_mul_f32_e32 v93, v81, v81
	v_mul_f32_e32 v94, v82, v82
	v_mul_f32_e32 v95, v83, v83
	v_fma_f32 v88, v88, s98, v250
	v_fma_f32 v89, v89, s98, v250
	v_fma_f32 v90, v90, s98, v250
	v_fma_f32 v91, v91, s98, v250
	v_fma_f32 v92, v92, s98, v250
	v_fma_f32 v93, v93, s98, v250
	v_fma_f32 v94, v94, s98, v250
	v_fma_f32 v95, v95, s98, v250
	v_mul_f32_e32 v88, v84, v88
	v_mul_f32_e32 v89, v85, v89
	v_mul_f32_e32 v90, v86, v90
	v_mul_f32_e32 v91, v87, v91
	v_mul_f32_e32 v92, v80, v92
	v_mul_f32_e32 v93, v81, v93
	v_mul_f32_e32 v94, v82, v94
	v_mul_f32_e32 v95, v83, v95
	v_exp_f32_e32 v88, v88
	v_exp_f32_e32 v89, v89
	v_exp_f32_e32 v90, v90
	v_exp_f32_e32 v91, v91
	v_exp_f32_e32 v92, v92
	v_exp_f32_e32 v93, v93
	v_exp_f32_e32 v94, v94
	v_exp_f32_e32 v95, v95
	v_add_f32_e32 v88, 1.0, v88
	v_add_f32_e32 v89, 1.0, v89
	v_add_f32_e32 v90, 1.0, v90
	v_add_f32_e32 v91, 1.0, v91
	v_add_f32_e32 v92, 1.0, v92
	v_add_f32_e32 v93, 1.0, v93
	v_add_f32_e32 v94, 1.0, v94
	v_add_f32_e32 v95, 1.0, v95
	v_rcp_f32_e32 v88, v88
	v_rcp_f32_e32 v89, v89
	v_rcp_f32_e32 v90, v90
	v_rcp_f32_e32 v91, v91
	v_rcp_f32_e32 v92, v92
	v_rcp_f32_e32 v93, v93
	v_rcp_f32_e32 v94, v94
	v_rcp_f32_e32 v95, v95
	v_mul_f32_e32 v88, v84, v88
	v_mul_f32_e32 v89, v85, v89
	v_mul_f32_e32 v90, v86, v90
	v_mul_f32_e32 v91, v87, v91
	v_mul_f32_e32 v92, v80, v92
	v_mul_f32_e32 v93, v81, v93
	v_mul_f32_e32 v94, v82, v94
	v_mul_f32_e32 v95, v83, v95
	v_cvt_pk_bf16_f32 v88, v88, v89
	v_cvt_pk_bf16_f32 v89, v90, v91
	v_cvt_pk_bf16_f32 v90, v92, v93
	v_cvt_pk_bf16_f32 v91, v94, v95
	global_store_dwordx4 v174, v[88:91], s[60:61] offset:256
	s_add_u32 s60, s60, s64
	s_addc_u32 s61, s61, 0
	v_mul_f32_e32 v80, v76, v76
	v_mul_f32_e32 v81, v77, v77
	v_mul_f32_e32 v82, v78, v78
	v_mul_f32_e32 v83, v79, v79
	v_mul_f32_e32 v84, v72, v72
	v_mul_f32_e32 v85, v73, v73
	v_mul_f32_e32 v86, v74, v74
	v_mul_f32_e32 v87, v75, v75
	v_fma_f32 v80, v80, s98, v250
	v_fma_f32 v81, v81, s98, v250
	v_fma_f32 v82, v82, s98, v250
	v_fma_f32 v83, v83, s98, v250
	v_fma_f32 v84, v84, s98, v250
	v_fma_f32 v85, v85, s98, v250
	v_fma_f32 v86, v86, s98, v250
	v_fma_f32 v87, v87, s98, v250
	v_mul_f32_e32 v80, v76, v80
	v_mul_f32_e32 v81, v77, v81
	v_mul_f32_e32 v82, v78, v82
	v_mul_f32_e32 v83, v79, v83
	v_mul_f32_e32 v84, v72, v84
	v_mul_f32_e32 v85, v73, v85
	v_mul_f32_e32 v86, v74, v86
	v_mul_f32_e32 v87, v75, v87
	v_exp_f32_e32 v80, v80
	v_exp_f32_e32 v81, v81
	v_exp_f32_e32 v82, v82
	v_exp_f32_e32 v83, v83
	v_exp_f32_e32 v84, v84
	v_exp_f32_e32 v85, v85
	v_exp_f32_e32 v86, v86
	v_exp_f32_e32 v87, v87
	v_add_f32_e32 v80, 1.0, v80
	v_add_f32_e32 v81, 1.0, v81
	v_add_f32_e32 v82, 1.0, v82
	v_add_f32_e32 v83, 1.0, v83
	v_add_f32_e32 v84, 1.0, v84
	v_add_f32_e32 v85, 1.0, v85
	v_add_f32_e32 v86, 1.0, v86
	v_add_f32_e32 v87, 1.0, v87
	v_rcp_f32_e32 v80, v80
	v_rcp_f32_e32 v81, v81
	v_rcp_f32_e32 v82, v82
	v_rcp_f32_e32 v83, v83
	v_rcp_f32_e32 v84, v84
	v_rcp_f32_e32 v85, v85
	v_rcp_f32_e32 v86, v86
	v_rcp_f32_e32 v87, v87
	v_mul_f32_e32 v80, v76, v80
	v_mul_f32_e32 v81, v77, v81
	v_mul_f32_e32 v82, v78, v82
	v_mul_f32_e32 v83, v79, v83
	v_mul_f32_e32 v84, v72, v84
	v_mul_f32_e32 v85, v73, v85
	v_mul_f32_e32 v86, v74, v86
	v_mul_f32_e32 v87, v75, v87
	v_cvt_pk_bf16_f32 v80, v80, v81
	v_cvt_pk_bf16_f32 v81, v82, v83
	v_cvt_pk_bf16_f32 v82, v84, v85
	v_cvt_pk_bf16_f32 v83, v86, v87
	global_store_dwordx4 v174, v[80:83], s[60:61]
	v_mul_f32_e32 v72, v68, v68
	v_mul_f32_e32 v73, v69, v69
	v_mul_f32_e32 v74, v70, v70
	v_mul_f32_e32 v75, v71, v71
	v_mul_f32_e32 v76, v64, v64
	v_mul_f32_e32 v77, v65, v65
	v_mul_f32_e32 v78, v66, v66
	v_mul_f32_e32 v79, v67, v67
	v_fma_f32 v72, v72, s98, v250
	v_fma_f32 v73, v73, s98, v250
	v_fma_f32 v74, v74, s98, v250
	v_fma_f32 v75, v75, s98, v250
	v_fma_f32 v76, v76, s98, v250
	v_fma_f32 v77, v77, s98, v250
	v_fma_f32 v78, v78, s98, v250
	v_fma_f32 v79, v79, s98, v250
	v_mul_f32_e32 v72, v68, v72
	v_mul_f32_e32 v73, v69, v73
	v_mul_f32_e32 v74, v70, v74
	v_mul_f32_e32 v75, v71, v75
	v_mul_f32_e32 v76, v64, v76
	v_mul_f32_e32 v77, v65, v77
	v_mul_f32_e32 v78, v66, v78
	v_mul_f32_e32 v79, v67, v79
	v_exp_f32_e32 v72, v72
	v_exp_f32_e32 v73, v73
	v_exp_f32_e32 v74, v74
	v_exp_f32_e32 v75, v75
	v_exp_f32_e32 v76, v76
	v_exp_f32_e32 v77, v77
	v_exp_f32_e32 v78, v78
	v_exp_f32_e32 v79, v79
	v_add_f32_e32 v72, 1.0, v72
	v_add_f32_e32 v73, 1.0, v73
	v_add_f32_e32 v74, 1.0, v74
	v_add_f32_e32 v75, 1.0, v75
	v_add_f32_e32 v76, 1.0, v76
	v_add_f32_e32 v77, 1.0, v77
	v_add_f32_e32 v78, 1.0, v78
	v_add_f32_e32 v79, 1.0, v79
	v_rcp_f32_e32 v72, v72
	v_rcp_f32_e32 v73, v73
	v_rcp_f32_e32 v74, v74
	v_rcp_f32_e32 v75, v75
	v_rcp_f32_e32 v76, v76
	v_rcp_f32_e32 v77, v77
	v_rcp_f32_e32 v78, v78
	v_rcp_f32_e32 v79, v79
	v_mul_f32_e32 v72, v68, v72
	v_mul_f32_e32 v73, v69, v73
	v_mul_f32_e32 v74, v70, v74
	v_mul_f32_e32 v75, v71, v75
	v_mul_f32_e32 v76, v64, v76
	v_mul_f32_e32 v77, v65, v77
	v_mul_f32_e32 v78, v66, v78
	v_mul_f32_e32 v79, v67, v79
	v_cvt_pk_bf16_f32 v72, v72, v73
	v_cvt_pk_bf16_f32 v73, v74, v75
	v_cvt_pk_bf16_f32 v74, v76, v77
	v_cvt_pk_bf16_f32 v75, v78, v79
	global_store_dwordx4 v174, v[72:75], s[60:61] offset:256
	s_add_u32 s60, s60, s64
	s_addc_u32 s61, s61, 0
	s_add_u32 s60, s60, s65
	s_addc_u32 s61, s61, 0
	v_mul_f32_e32 v64, v60, v60
	v_mul_f32_e32 v65, v61, v61
	v_mul_f32_e32 v66, v62, v62
	v_mul_f32_e32 v67, v63, v63
	v_mul_f32_e32 v68, v56, v56
	v_mul_f32_e32 v69, v57, v57
	v_mul_f32_e32 v70, v58, v58
	v_mul_f32_e32 v71, v59, v59
	v_fma_f32 v64, v64, s98, v250
	v_fma_f32 v65, v65, s98, v250
	v_fma_f32 v66, v66, s98, v250
	v_fma_f32 v67, v67, s98, v250
	v_fma_f32 v68, v68, s98, v250
	v_fma_f32 v69, v69, s98, v250
	v_fma_f32 v70, v70, s98, v250
	v_fma_f32 v71, v71, s98, v250
	v_mul_f32_e32 v64, v60, v64
	v_mul_f32_e32 v65, v61, v65
	v_mul_f32_e32 v66, v62, v66
	v_mul_f32_e32 v67, v63, v67
	v_mul_f32_e32 v68, v56, v68
	v_mul_f32_e32 v69, v57, v69
	v_mul_f32_e32 v70, v58, v70
	v_mul_f32_e32 v71, v59, v71
	v_exp_f32_e32 v64, v64
	v_exp_f32_e32 v65, v65
	v_exp_f32_e32 v66, v66
	v_exp_f32_e32 v67, v67
	v_exp_f32_e32 v68, v68
	v_exp_f32_e32 v69, v69
	v_exp_f32_e32 v70, v70
	v_exp_f32_e32 v71, v71
	v_add_f32_e32 v64, 1.0, v64
	v_add_f32_e32 v65, 1.0, v65
	v_add_f32_e32 v66, 1.0, v66
	v_add_f32_e32 v67, 1.0, v67
	v_add_f32_e32 v68, 1.0, v68
	v_add_f32_e32 v69, 1.0, v69
	v_add_f32_e32 v70, 1.0, v70
	v_add_f32_e32 v71, 1.0, v71
	v_rcp_f32_e32 v64, v64
	v_rcp_f32_e32 v65, v65
	v_rcp_f32_e32 v66, v66
	v_rcp_f32_e32 v67, v67
	v_rcp_f32_e32 v68, v68
	v_rcp_f32_e32 v69, v69
	v_rcp_f32_e32 v70, v70
	v_rcp_f32_e32 v71, v71
	v_mul_f32_e32 v64, v60, v64
	v_mul_f32_e32 v65, v61, v65
	v_mul_f32_e32 v66, v62, v66
	v_mul_f32_e32 v67, v63, v67
	v_mul_f32_e32 v68, v56, v68
	v_mul_f32_e32 v69, v57, v69
	v_mul_f32_e32 v70, v58, v70
	v_mul_f32_e32 v71, v59, v71
	v_cvt_pk_bf16_f32 v64, v64, v65
	v_cvt_pk_bf16_f32 v65, v66, v67
	v_cvt_pk_bf16_f32 v66, v68, v69
	v_cvt_pk_bf16_f32 v67, v70, v71
	global_store_dwordx4 v174, v[64:67], s[60:61]
	v_mul_f32_e32 v56, v52, v52
	v_mul_f32_e32 v57, v53, v53
	v_mul_f32_e32 v58, v54, v54
	v_mul_f32_e32 v59, v55, v55
	v_mul_f32_e32 v60, v48, v48
	v_mul_f32_e32 v61, v49, v49
	v_mul_f32_e32 v62, v50, v50
	v_mul_f32_e32 v63, v51, v51
	v_fma_f32 v56, v56, s98, v250
	v_fma_f32 v57, v57, s98, v250
	v_fma_f32 v58, v58, s98, v250
	v_fma_f32 v59, v59, s98, v250
	v_fma_f32 v60, v60, s98, v250
	v_fma_f32 v61, v61, s98, v250
	v_fma_f32 v62, v62, s98, v250
	v_fma_f32 v63, v63, s98, v250
	v_mul_f32_e32 v56, v52, v56
	v_mul_f32_e32 v57, v53, v57
	v_mul_f32_e32 v58, v54, v58
	v_mul_f32_e32 v59, v55, v59
	v_mul_f32_e32 v60, v48, v60
	v_mul_f32_e32 v61, v49, v61
	v_mul_f32_e32 v62, v50, v62
	v_mul_f32_e32 v63, v51, v63
	v_exp_f32_e32 v56, v56
	v_exp_f32_e32 v57, v57
	v_exp_f32_e32 v58, v58
	v_exp_f32_e32 v59, v59
	v_exp_f32_e32 v60, v60
	v_exp_f32_e32 v61, v61
	v_exp_f32_e32 v62, v62
	v_exp_f32_e32 v63, v63
	v_add_f32_e32 v56, 1.0, v56
	v_add_f32_e32 v57, 1.0, v57
	v_add_f32_e32 v58, 1.0, v58
	v_add_f32_e32 v59, 1.0, v59
	v_add_f32_e32 v60, 1.0, v60
	v_add_f32_e32 v61, 1.0, v61
	v_add_f32_e32 v62, 1.0, v62
	v_add_f32_e32 v63, 1.0, v63
	v_rcp_f32_e32 v56, v56
	v_rcp_f32_e32 v57, v57
	v_rcp_f32_e32 v58, v58
	v_rcp_f32_e32 v59, v59
	v_rcp_f32_e32 v60, v60
	v_rcp_f32_e32 v61, v61
	v_rcp_f32_e32 v62, v62
	v_rcp_f32_e32 v63, v63
	v_mul_f32_e32 v56, v52, v56
	v_mul_f32_e32 v57, v53, v57
	v_mul_f32_e32 v58, v54, v58
	v_mul_f32_e32 v59, v55, v59
	v_mul_f32_e32 v60, v48, v60
	v_mul_f32_e32 v61, v49, v61
	v_mul_f32_e32 v62, v50, v62
	v_mul_f32_e32 v63, v51, v63
	v_cvt_pk_bf16_f32 v56, v56, v57
	v_cvt_pk_bf16_f32 v57, v58, v59
	v_cvt_pk_bf16_f32 v58, v60, v61
	v_cvt_pk_bf16_f32 v59, v62, v63
	global_store_dwordx4 v174, v[56:59], s[60:61] offset:256
	s_add_u32 s60, s60, s64
	s_addc_u32 s61, s61, 0
	v_mul_f32_e32 v48, v44, v44
	v_mul_f32_e32 v49, v45, v45
	v_mul_f32_e32 v50, v46, v46
	v_mul_f32_e32 v51, v47, v47
	v_mul_f32_e32 v52, v40, v40
	v_mul_f32_e32 v53, v41, v41
	v_mul_f32_e32 v54, v42, v42
	v_mul_f32_e32 v55, v43, v43
	v_fma_f32 v48, v48, s98, v250
	v_fma_f32 v49, v49, s98, v250
	v_fma_f32 v50, v50, s98, v250
	v_fma_f32 v51, v51, s98, v250
	v_fma_f32 v52, v52, s98, v250
	v_fma_f32 v53, v53, s98, v250
	v_fma_f32 v54, v54, s98, v250
	v_fma_f32 v55, v55, s98, v250
	v_mul_f32_e32 v48, v44, v48
	v_mul_f32_e32 v49, v45, v49
	v_mul_f32_e32 v50, v46, v50
	v_mul_f32_e32 v51, v47, v51
	v_mul_f32_e32 v52, v40, v52
	v_mul_f32_e32 v53, v41, v53
	v_mul_f32_e32 v54, v42, v54
	v_mul_f32_e32 v55, v43, v55
	v_exp_f32_e32 v48, v48
	v_exp_f32_e32 v49, v49
	v_exp_f32_e32 v50, v50
	v_exp_f32_e32 v51, v51
	v_exp_f32_e32 v52, v52
	v_exp_f32_e32 v53, v53
	v_exp_f32_e32 v54, v54
	v_exp_f32_e32 v55, v55
	v_add_f32_e32 v48, 1.0, v48
	v_add_f32_e32 v49, 1.0, v49
	v_add_f32_e32 v50, 1.0, v50
	v_add_f32_e32 v51, 1.0, v51
	v_add_f32_e32 v52, 1.0, v52
	v_add_f32_e32 v53, 1.0, v53
	v_add_f32_e32 v54, 1.0, v54
	v_add_f32_e32 v55, 1.0, v55
	v_rcp_f32_e32 v48, v48
	v_rcp_f32_e32 v49, v49
	v_rcp_f32_e32 v50, v50
	v_rcp_f32_e32 v51, v51
	v_rcp_f32_e32 v52, v52
	v_rcp_f32_e32 v53, v53
	v_rcp_f32_e32 v54, v54
	v_rcp_f32_e32 v55, v55
	v_mul_f32_e32 v48, v44, v48
	v_mul_f32_e32 v49, v45, v49
	v_mul_f32_e32 v50, v46, v50
	v_mul_f32_e32 v51, v47, v51
	v_mul_f32_e32 v52, v40, v52
	v_mul_f32_e32 v53, v41, v53
	v_mul_f32_e32 v54, v42, v54
	v_mul_f32_e32 v55, v43, v55
	v_cvt_pk_bf16_f32 v48, v48, v49
	v_cvt_pk_bf16_f32 v49, v50, v51
	v_cvt_pk_bf16_f32 v50, v52, v53
	v_cvt_pk_bf16_f32 v51, v54, v55
	global_store_dwordx4 v174, v[48:51], s[60:61]
	v_mul_f32_e32 v40, v36, v36
	v_mul_f32_e32 v41, v37, v37
	v_mul_f32_e32 v42, v38, v38
	v_mul_f32_e32 v43, v39, v39
	v_mul_f32_e32 v44, v32, v32
	v_mul_f32_e32 v45, v33, v33
	v_mul_f32_e32 v46, v34, v34
	v_mul_f32_e32 v47, v35, v35
	v_fma_f32 v40, v40, s98, v250
	v_fma_f32 v41, v41, s98, v250
	v_fma_f32 v42, v42, s98, v250
	v_fma_f32 v43, v43, s98, v250
	v_fma_f32 v44, v44, s98, v250
	v_fma_f32 v45, v45, s98, v250
	v_fma_f32 v46, v46, s98, v250
	v_fma_f32 v47, v47, s98, v250
	v_mul_f32_e32 v40, v36, v40
	v_mul_f32_e32 v41, v37, v41
	v_mul_f32_e32 v42, v38, v42
	v_mul_f32_e32 v43, v39, v43
	v_mul_f32_e32 v44, v32, v44
	v_mul_f32_e32 v45, v33, v45
	v_mul_f32_e32 v46, v34, v46
	v_mul_f32_e32 v47, v35, v47
	v_exp_f32_e32 v40, v40
	v_exp_f32_e32 v41, v41
	v_exp_f32_e32 v42, v42
	v_exp_f32_e32 v43, v43
	v_exp_f32_e32 v44, v44
	v_exp_f32_e32 v45, v45
	v_exp_f32_e32 v46, v46
	v_exp_f32_e32 v47, v47
	v_add_f32_e32 v40, 1.0, v40
	v_add_f32_e32 v41, 1.0, v41
	v_add_f32_e32 v42, 1.0, v42
	v_add_f32_e32 v43, 1.0, v43
	v_add_f32_e32 v44, 1.0, v44
	v_add_f32_e32 v45, 1.0, v45
	v_add_f32_e32 v46, 1.0, v46
	v_add_f32_e32 v47, 1.0, v47
	v_rcp_f32_e32 v40, v40
	v_rcp_f32_e32 v41, v41
	v_rcp_f32_e32 v42, v42
	v_rcp_f32_e32 v43, v43
	v_rcp_f32_e32 v44, v44
	v_rcp_f32_e32 v45, v45
	v_rcp_f32_e32 v46, v46
	v_rcp_f32_e32 v47, v47
	v_mul_f32_e32 v40, v36, v40
	v_mul_f32_e32 v41, v37, v41
	v_mul_f32_e32 v42, v38, v42
	v_mul_f32_e32 v43, v39, v43
	v_mul_f32_e32 v44, v32, v44
	v_mul_f32_e32 v45, v33, v45
	v_mul_f32_e32 v46, v34, v46
	v_mul_f32_e32 v47, v35, v47
	v_cvt_pk_bf16_f32 v40, v40, v41
	v_cvt_pk_bf16_f32 v41, v42, v43
	v_cvt_pk_bf16_f32 v42, v44, v45
	v_cvt_pk_bf16_f32 v43, v46, v47
	global_store_dwordx4 v174, v[40:43], s[60:61] offset:256
	s_add_u32 s60, s60, s64
	s_addc_u32 s61, s61, 0
	v_mul_f32_e32 v32, v28, v28
	v_mul_f32_e32 v33, v29, v29
	v_mul_f32_e32 v34, v30, v30
	v_mul_f32_e32 v35, v31, v31
	v_mul_f32_e32 v36, v24, v24
	v_mul_f32_e32 v37, v25, v25
	v_mul_f32_e32 v38, v26, v26
	v_mul_f32_e32 v39, v27, v27
	v_fma_f32 v32, v32, s98, v250
	v_fma_f32 v33, v33, s98, v250
	v_fma_f32 v34, v34, s98, v250
	v_fma_f32 v35, v35, s98, v250
	v_fma_f32 v36, v36, s98, v250
	v_fma_f32 v37, v37, s98, v250
	v_fma_f32 v38, v38, s98, v250
	v_fma_f32 v39, v39, s98, v250
	v_mul_f32_e32 v32, v28, v32
	v_mul_f32_e32 v33, v29, v33
	v_mul_f32_e32 v34, v30, v34
	v_mul_f32_e32 v35, v31, v35
	v_mul_f32_e32 v36, v24, v36
	v_mul_f32_e32 v37, v25, v37
	v_mul_f32_e32 v38, v26, v38
	v_mul_f32_e32 v39, v27, v39
	v_exp_f32_e32 v32, v32
	v_exp_f32_e32 v33, v33
	v_exp_f32_e32 v34, v34
	v_exp_f32_e32 v35, v35
	v_exp_f32_e32 v36, v36
	v_exp_f32_e32 v37, v37
	v_exp_f32_e32 v38, v38
	v_exp_f32_e32 v39, v39
	v_add_f32_e32 v32, 1.0, v32
	v_add_f32_e32 v33, 1.0, v33
	v_add_f32_e32 v34, 1.0, v34
	v_add_f32_e32 v35, 1.0, v35
	v_add_f32_e32 v36, 1.0, v36
	v_add_f32_e32 v37, 1.0, v37
	v_add_f32_e32 v38, 1.0, v38
	v_add_f32_e32 v39, 1.0, v39
	v_rcp_f32_e32 v32, v32
	v_rcp_f32_e32 v33, v33
	v_rcp_f32_e32 v34, v34
	v_rcp_f32_e32 v35, v35
	v_rcp_f32_e32 v36, v36
	v_rcp_f32_e32 v37, v37
	v_rcp_f32_e32 v38, v38
	v_rcp_f32_e32 v39, v39
	v_mul_f32_e32 v32, v28, v32
	v_mul_f32_e32 v33, v29, v33
	v_mul_f32_e32 v34, v30, v34
	v_mul_f32_e32 v35, v31, v35
	v_mul_f32_e32 v36, v24, v36
	v_mul_f32_e32 v37, v25, v37
	v_mul_f32_e32 v38, v26, v38
	v_mul_f32_e32 v39, v27, v39
	v_cvt_pk_bf16_f32 v32, v32, v33
	v_cvt_pk_bf16_f32 v33, v34, v35
	v_cvt_pk_bf16_f32 v34, v36, v37
	v_cvt_pk_bf16_f32 v35, v38, v39
	global_store_dwordx4 v174, v[32:35], s[60:61]
	v_mul_f32_e32 v24, v20, v20
	v_mul_f32_e32 v25, v21, v21
	v_mul_f32_e32 v26, v22, v22
	v_mul_f32_e32 v27, v23, v23
	v_mul_f32_e32 v28, v16, v16
	v_mul_f32_e32 v29, v17, v17
	v_mul_f32_e32 v30, v18, v18
	v_mul_f32_e32 v31, v19, v19
	v_fma_f32 v24, v24, s98, v250
	v_fma_f32 v25, v25, s98, v250
	v_fma_f32 v26, v26, s98, v250
	v_fma_f32 v27, v27, s98, v250
	v_fma_f32 v28, v28, s98, v250
	v_fma_f32 v29, v29, s98, v250
	v_fma_f32 v30, v30, s98, v250
	v_fma_f32 v31, v31, s98, v250
	v_mul_f32_e32 v24, v20, v24
	v_mul_f32_e32 v25, v21, v25
	v_mul_f32_e32 v26, v22, v26
	v_mul_f32_e32 v27, v23, v27
	v_mul_f32_e32 v28, v16, v28
	v_mul_f32_e32 v29, v17, v29
	v_mul_f32_e32 v30, v18, v30
	v_mul_f32_e32 v31, v19, v31
	v_exp_f32_e32 v24, v24
	v_exp_f32_e32 v25, v25
	v_exp_f32_e32 v26, v26
	v_exp_f32_e32 v27, v27
	v_exp_f32_e32 v28, v28
	v_exp_f32_e32 v29, v29
	v_exp_f32_e32 v30, v30
	v_exp_f32_e32 v31, v31
	v_add_f32_e32 v24, 1.0, v24
	v_add_f32_e32 v25, 1.0, v25
	v_add_f32_e32 v26, 1.0, v26
	v_add_f32_e32 v27, 1.0, v27
	v_add_f32_e32 v28, 1.0, v28
	v_add_f32_e32 v29, 1.0, v29
	v_add_f32_e32 v30, 1.0, v30
	v_add_f32_e32 v31, 1.0, v31
	v_rcp_f32_e32 v24, v24
	v_rcp_f32_e32 v25, v25
	v_rcp_f32_e32 v26, v26
	v_rcp_f32_e32 v27, v27
	v_rcp_f32_e32 v28, v28
	v_rcp_f32_e32 v29, v29
	v_rcp_f32_e32 v30, v30
	v_rcp_f32_e32 v31, v31
	v_mul_f32_e32 v24, v20, v24
	v_mul_f32_e32 v25, v21, v25
	v_mul_f32_e32 v26, v22, v26
	v_mul_f32_e32 v27, v23, v27
	v_mul_f32_e32 v28, v16, v28
	v_mul_f32_e32 v29, v17, v29
	v_mul_f32_e32 v30, v18, v30
	v_mul_f32_e32 v31, v19, v31
	v_cvt_pk_bf16_f32 v24, v24, v25
	v_cvt_pk_bf16_f32 v25, v26, v27
	v_cvt_pk_bf16_f32 v26, v28, v29
	v_cvt_pk_bf16_f32 v27, v30, v31
	global_store_dwordx4 v174, v[24:27], s[60:61] offset:256
	s_add_u32 s60, s60, s64
	s_addc_u32 s61, s61, 0
	v_mul_f32_e32 v16, v12, v12
	v_mul_f32_e32 v17, v13, v13
	v_mul_f32_e32 v18, v14, v14
	v_mul_f32_e32 v19, v15, v15
	v_mul_f32_e32 v20, v8, v8
	v_mul_f32_e32 v21, v9, v9
	v_mul_f32_e32 v22, v10, v10
	v_mul_f32_e32 v23, v11, v11
	v_fma_f32 v16, v16, s98, v250
	v_fma_f32 v17, v17, s98, v250
	v_fma_f32 v18, v18, s98, v250
	v_fma_f32 v19, v19, s98, v250
	v_fma_f32 v20, v20, s98, v250
	v_fma_f32 v21, v21, s98, v250
	v_fma_f32 v22, v22, s98, v250
	v_fma_f32 v23, v23, s98, v250
	v_mul_f32_e32 v16, v12, v16
	v_mul_f32_e32 v17, v13, v17
	v_mul_f32_e32 v18, v14, v18
	v_mul_f32_e32 v19, v15, v19
	v_mul_f32_e32 v20, v8, v20
	v_mul_f32_e32 v21, v9, v21
	v_mul_f32_e32 v22, v10, v22
	v_mul_f32_e32 v23, v11, v23
	v_exp_f32_e32 v16, v16
	v_exp_f32_e32 v17, v17
	v_exp_f32_e32 v18, v18
	v_exp_f32_e32 v19, v19
	v_exp_f32_e32 v20, v20
	v_exp_f32_e32 v21, v21
	v_exp_f32_e32 v22, v22
	v_exp_f32_e32 v23, v23
	v_add_f32_e32 v16, 1.0, v16
	v_add_f32_e32 v17, 1.0, v17
	v_add_f32_e32 v18, 1.0, v18
	v_add_f32_e32 v19, 1.0, v19
	v_add_f32_e32 v20, 1.0, v20
	v_add_f32_e32 v21, 1.0, v21
	v_add_f32_e32 v22, 1.0, v22
	v_add_f32_e32 v23, 1.0, v23
	v_rcp_f32_e32 v16, v16
	v_rcp_f32_e32 v17, v17
	v_rcp_f32_e32 v18, v18
	v_rcp_f32_e32 v19, v19
	v_rcp_f32_e32 v20, v20
	v_rcp_f32_e32 v21, v21
	v_rcp_f32_e32 v22, v22
	v_rcp_f32_e32 v23, v23
	v_mul_f32_e32 v16, v12, v16
	v_mul_f32_e32 v17, v13, v17
	v_mul_f32_e32 v18, v14, v18
	v_mul_f32_e32 v19, v15, v19
	v_mul_f32_e32 v20, v8, v20
	v_mul_f32_e32 v21, v9, v21
	v_mul_f32_e32 v22, v10, v22
	v_mul_f32_e32 v23, v11, v23
	v_cvt_pk_bf16_f32 v16, v16, v17
	v_cvt_pk_bf16_f32 v17, v18, v19
	v_cvt_pk_bf16_f32 v18, v20, v21
	v_cvt_pk_bf16_f32 v19, v22, v23
	global_store_dwordx4 v174, v[16:19], s[60:61]
	v_mul_f32_e32 v8, v4, v4
	v_mul_f32_e32 v9, v5, v5
	v_mul_f32_e32 v10, v6, v6
	v_mul_f32_e32 v11, v7, v7
	v_mul_f32_e32 v12, v0, v0
	v_mul_f32_e32 v13, v1, v1
	v_mul_f32_e32 v14, v2, v2
	v_mul_f32_e32 v15, v3, v3
	v_fma_f32 v8, v8, s98, v250
	v_fma_f32 v9, v9, s98, v250
	v_fma_f32 v10, v10, s98, v250
	v_fma_f32 v11, v11, s98, v250
	v_fma_f32 v12, v12, s98, v250
	v_fma_f32 v13, v13, s98, v250
	v_fma_f32 v14, v14, s98, v250
	v_fma_f32 v15, v15, s98, v250
	v_mul_f32_e32 v8, v4, v8
	v_mul_f32_e32 v9, v5, v9
	v_mul_f32_e32 v10, v6, v10
	v_mul_f32_e32 v11, v7, v11
	v_mul_f32_e32 v12, v0, v12
	v_mul_f32_e32 v13, v1, v13
	v_mul_f32_e32 v14, v2, v14
	v_mul_f32_e32 v15, v3, v15
	v_exp_f32_e32 v8, v8
	v_exp_f32_e32 v9, v9
	v_exp_f32_e32 v10, v10
	v_exp_f32_e32 v11, v11
	v_exp_f32_e32 v12, v12
	v_exp_f32_e32 v13, v13
	v_exp_f32_e32 v14, v14
	v_exp_f32_e32 v15, v15
	v_add_f32_e32 v8, 1.0, v8
	v_add_f32_e32 v9, 1.0, v9
	v_add_f32_e32 v10, 1.0, v10
	v_add_f32_e32 v11, 1.0, v11
	v_add_f32_e32 v12, 1.0, v12
	v_add_f32_e32 v13, 1.0, v13
	v_add_f32_e32 v14, 1.0, v14
	v_add_f32_e32 v15, 1.0, v15
	v_rcp_f32_e32 v8, v8
	v_rcp_f32_e32 v9, v9
	v_rcp_f32_e32 v10, v10
	v_rcp_f32_e32 v11, v11
	v_rcp_f32_e32 v12, v12
	v_rcp_f32_e32 v13, v13
	v_rcp_f32_e32 v14, v14
	v_rcp_f32_e32 v15, v15
	v_mul_f32_e32 v8, v4, v8
	v_mul_f32_e32 v9, v5, v9
	v_mul_f32_e32 v10, v6, v10
	v_mul_f32_e32 v11, v7, v11
	v_mul_f32_e32 v12, v0, v12
	v_mul_f32_e32 v13, v1, v13
	v_mul_f32_e32 v14, v2, v14
	v_mul_f32_e32 v15, v3, v15
	v_cvt_pk_bf16_f32 v8, v8, v9
	v_cvt_pk_bf16_f32 v9, v10, v11
	v_cvt_pk_bf16_f32 v10, v12, v13
	v_cvt_pk_bf16_f32 v11, v14, v15
	global_store_dwordx4 v174, v[8:11], s[60:61] offset:256
	s_branch .Lwin_done
